# baseline (speedup 1.0000x reference)
.LBB0_389:
	v_cmp_eq_f32_e32 vcc, 0, v238
	v_cmp_eq_f32_e64 s[10:11], 0, v237
	s_and_b64 vcc, vcc, s[10:11]
	s_and_b32 s27, s86, 0xc000
	v_add_u32_e32 v241, s27, v233
	v_xor_b32_e32 v240, 32, v241
	v_xor_b32_e32 v239, 64, v241
	v_xor_b32_e32 v0, 0x60, v241
	s_cmp_gt_u32 s87, 29
	s_cbranch_scc1 .Ltail_c0
	s_add_i32 s3, s86, 0x8000
	s_and_b32 s3, s3, 0xc000
	s_add_u32 s0, s84, s56
	s_addc_u32 s1, s85, s57
	s_add_u32 s10, s0, s40
	s_addc_u32 s11, s1, s41
	s_add_u32 s0, s0, s18
	s_addc_u32 s1, s1, s19
	s_add_i32 m0, s81, s3
	s_nop 0
	global_load_lds_dwordx4 v250, s[0:1]
	s_add_i32 m0, s80, s3
	s_add_i32 s3, s3, 0x2000
	global_load_lds_dwordx4 v251, s[10:11]
	s_add_u32 s0, s0, 0xb8000
	s_addc_u32 s1, s1, 0
	s_add_i32 m0, s81, s3
	s_add_u32 s10, s10, 0xb8000
	s_addc_u32 s11, s11, 0
	global_load_lds_dwordx4 v250, s[0:1]
	s_add_i32 m0, s80, s3
	s_nop 0
	global_load_lds_dwordx4 v251, s[10:11]
	s_waitcnt vmcnt(8)

.LBB0_395:
.Lfz1_c0:
	ds_read_b128 v[144:147], v241 offset:0
	ds_read_b128 v[148:151], v240 offset:0
	ds_read_b128 v[152:155], v239 offset:0
	ds_read_b128 v[156:159], v0 offset:0
	s_waitcnt lgkmcnt(0)
	v_mfma_f32_32x32x16_bf16 v[212:227], v[144:147], v[176:179], 0
	v_mfma_f32_32x32x16_bf16 v[212:227], v[148:151], v[180:183], v[212:227]
	v_mfma_f32_32x32x16_bf16 v[212:227], v[152:155], v[184:187], v[212:227]
	v_mfma_f32_32x32x16_bf16 v[212:227], v[156:159], v[188:191], v[212:227]
	ds_read_b128 v[144:147], v241 offset:0x80
	ds_read_b128 v[148:151], v240 offset:0x80
	ds_read_b128 v[152:155], v239 offset:0x80
	ds_read_b128 v[156:159], v0 offset:0x80
	s_cmp_eq_u64 vcc, exec
	s_waitcnt lgkmcnt(0)
	v_mfma_f32_32x32x16_bf16 v[160:175], v[144:147], v[192:195], 0
	v_mfma_f32_32x32x16_bf16 v[160:175], v[148:151], v[196:199], v[160:175]
	v_mfma_f32_32x32x16_bf16 v[160:175], v[152:155], v[200:203], v[160:175]
	v_mfma_f32_32x32x16_bf16 v[160:175], v[156:159], v[204:207], v[160:175]
	s_cbranch_scc0 .LBB0_397
	s_nop 0
	v_exp_f32_e32 v144, v212
	v_exp_f32_e32 v145, v213
	v_exp_f32_e32 v146, v214
	v_exp_f32_e32 v147, v215
	v_exp_f32_e32 v148, v216
	v_exp_f32_e32 v149, v217
	v_exp_f32_e32 v150, v218
	v_exp_f32_e32 v151, v219
	v_exp_f32_e32 v152, v220
	v_exp_f32_e32 v153, v221
	v_exp_f32_e32 v154, v222
	v_exp_f32_e32 v155, v223
	v_exp_f32_e32 v156, v224
	v_exp_f32_e32 v157, v225
	v_exp_f32_e32 v158, v226
	v_exp_f32_e32 v159, v227
	v_add_f32_e32 v252, v144, v145
	v_add_f32_e32 v253, v146, v147
	v_add_f32_e32 v254, v148, v149
	v_add_f32_e32 v255, v150, v151
	v_add_f32_e32 v252, v252, v152
	v_add_f32_e32 v253, v253, v153
	v_add_f32_e32 v254, v254, v154
	v_add_f32_e32 v255, v255, v155
	v_add_f32_e32 v252, v252, v156
	v_add_f32_e32 v253, v253, v157
	v_add_f32_e32 v254, v254, v158
	v_add_f32_e32 v255, v255, v159
	v_cvt_pk_bf16_f32 v216, v144, v145
	v_cvt_pk_bf16_f32 v217, v146, v147
	v_add_f32_e32 v252, v252, v253
	v_add_f32_e32 v254, v254, v255
	v_cvt_pk_bf16_f32 v218, v148, v149
	v_cvt_pk_bf16_f32 v219, v150, v151
	v_cvt_pk_bf16_f32 v224, v152, v153
	v_add_f32_e32 v252, v252, v254
	v_cvt_pk_bf16_f32 v225, v154, v155
	v_cvt_pk_bf16_f32 v226, v156, v157
	v_cvt_pk_bf16_f32 v227, v158, v159
	v_add_u32_e32 v253, 0xde801b54, v252
	v_cmp_gt_u32_e32 vcc, 0x3bff7543, v253
	s_cmp_lg_u64 vcc, exec
	s_cbranch_scc1 .LBB0_432
	v_add_f32_e32 v15, v15, v252
	v_exp_f32_e32 v144, v160
	v_exp_f32_e32 v145, v161
	v_exp_f32_e32 v146, v162
	v_exp_f32_e32 v147, v163
	v_exp_f32_e32 v148, v164
	v_exp_f32_e32 v149, v165
	v_exp_f32_e32 v150, v166
	v_exp_f32_e32 v151, v167
	v_exp_f32_e32 v152, v168
	v_exp_f32_e32 v153, v169
	v_exp_f32_e32 v154, v170
	v_exp_f32_e32 v155, v171
	v_exp_f32_e32 v156, v172
	v_exp_f32_e32 v157, v173
	v_exp_f32_e32 v158, v174
	v_exp_f32_e32 v159, v175
	v_add_f32_e32 v252, v144, v145
	v_add_f32_e32 v253, v146, v147
	v_add_f32_e32 v254, v148, v149
	v_add_f32_e32 v255, v150, v151
	v_add_f32_e32 v252, v252, v152
	v_add_f32_e32 v253, v253, v153
	v_add_f32_e32 v254, v254, v154
	v_add_f32_e32 v255, v255, v155
	v_add_f32_e32 v252, v252, v156
	v_add_f32_e32 v253, v253, v157
	v_add_f32_e32 v254, v254, v158
	v_add_f32_e32 v255, v255, v159
	v_cvt_pk_bf16_f32 v212, v144, v145
	v_cvt_pk_bf16_f32 v213, v146, v147
	v_add_f32_e32 v252, v252, v253
	v_add_f32_e32 v254, v254, v255
	v_cvt_pk_bf16_f32 v214, v148, v149
	v_cvt_pk_bf16_f32 v215, v150, v151
	v_cvt_pk_bf16_f32 v220, v152, v153
	v_add_f32_e32 v252, v252, v254
	v_cvt_pk_bf16_f32 v221, v154, v155
	v_cvt_pk_bf16_f32 v222, v156, v157
	v_cvt_pk_bf16_f32 v223, v158, v159
	v_add_u32_e32 v253, 0xde801b54, v252
	v_cmp_gt_u32_e32 vcc, 0x3bff7543, v253
	s_cmp_lg_u64 vcc, exec
	s_cbranch_scc1 .Lfzsb1_c0
	v_add_f32_e32 v14, v14, v252

.LBB0_1243:
	v_cmp_eq_f32_e32 vcc, 0, v238
	v_cmp_eq_f32_e64 s[10:11], 0, v237
	s_and_b64 vcc, vcc, s[10:11]
	s_and_b32 s27, s77, 0xc000
	v_add_u32_e32 v241, s27, v233
	v_xor_b32_e32 v240, 32, v241
	v_xor_b32_e32 v239, 64, v241
	v_xor_b32_e32 v0, 0x60, v241
	s_cmpk_gt_u32 s79, 0xfd
	s_cbranch_scc1 .Ltail_c1
	s_add_i32 s3, s77, 0x8000
	s_and_b32 s3, s3, 0xc000
	s_add_u32 s0, s69, s86
	s_addc_u32 s1, s76, s87
	s_add_u32 s10, s0, s36
	s_addc_u32 s11, s1, s37
	s_add_u32 s0, s0, s16
	s_addc_u32 s1, s1, s17
	s_add_i32 m0, s68, s3
	s_nop 0
	global_load_lds_dwordx4 v250, s[0:1]
	s_add_i32 m0, s57, s3
	s_add_i32 s3, s3, 0x2000
	global_load_lds_dwordx4 v251, s[10:11]
	s_add_u32 s0, s0, 0xb8000
	s_addc_u32 s1, s1, 0
	s_add_i32 m0, s68, s3
	s_add_u32 s10, s10, 0xb8000
	s_addc_u32 s11, s11, 0
	global_load_lds_dwordx4 v250, s[0:1]
	s_add_i32 m0, s57, s3
	s_nop 0
	global_load_lds_dwordx4 v251, s[10:11]
	s_waitcnt vmcnt(8)

.LBB0_2097:
	v_cmp_eq_f32_e32 vcc, 0, v238
	v_cmp_eq_f32_e64 s[6:7], 0, v237
	s_and_b64 vcc, vcc, s[6:7]
	s_and_b32 s27, s68, 0xc000
	v_add_u32_e32 v241, s27, v233
	v_xor_b32_e32 v240, 32, v241
	v_xor_b32_e32 v239, 64, v241
	v_xor_b32_e32 v0, 0x60, v241
	s_cmpk_gt_u32 s69, 0xfd
	s_cbranch_scc1 .Ltail_c2
	s_add_i32 s3, s68, 0x8000
	s_and_b32 s3, s3, 0xc000
	s_add_u32 s0, s66, s58
	s_addc_u32 s1, s67, s59
	s_add_u32 s6, s0, s16
	s_addc_u32 s7, s1, s17
	s_add_u32 s0, s0, s14
	s_addc_u32 s1, s1, s15
	s_add_i32 m0, s65, s3
	s_nop 0
	global_load_lds_dwordx4 v250, s[0:1]
	s_add_i32 m0, s64, s3
	s_add_i32 s3, s3, 0x2000
	global_load_lds_dwordx4 v251, s[6:7]
	s_add_u32 s0, s0, 0xb8000
	s_addc_u32 s1, s1, 0
	s_add_i32 m0, s65, s3
	s_add_u32 s6, s6, 0xb8000
	s_addc_u32 s7, s7, 0
	global_load_lds_dwordx4 v250, s[0:1]
	s_add_i32 m0, s64, s3
	s_nop 0
	global_load_lds_dwordx4 v251, s[6:7]
	s_waitcnt vmcnt(8)
